# scan pass B: 32 loads of each 8-step batch issued up front with counted vmcnt waits per step
# speedup vs baseline: 1.0047x; 1.0047x over previous
.LBB0_1021:
	v_lshl_add_u64 v[140:141], v[134:135], 0, v[188:189]
	v_add_co_u32_e32 v142, vcc, 0x23a00000, v140
	s_mov_b32 s1, 0x1ba01000
	s_nop 0
	v_addc_co_u32_e32 v143, vcc, 0, v141, vcc
	v_add_co_u32_e32 v142, vcc, 0x23a01000, v140
	s_mov_b64 s[6:7], 0x8000
	s_nop 0
	v_addc_co_u32_e32 v143, vcc, 0, v141, vcc
	v_lshl_add_u64 v[142:143], v[132:133], 0, v[188:189]
	s_mov_b32 s99, 0
	s_mov_b32 s98, 0x23a00800
	v_lshl_add_u64 v[144:145], v[140:141], 0, s[98:99]
	global_load_dwordx2 v[162:163], v[144:145], off offset:-2048
	global_load_dwordx2 v[164:165], v[144:145], off offset:2048
	s_mov_b32 s98, 0x1fa00800
	v_lshl_add_u64 v[148:149], v[142:143], 0, s[98:99]
	global_load_dwordx2 v[166:167], v[148:149], off offset:-2048
	s_mov_b32 s98, 0x1ba01000
	v_lshl_add_u64 v[146:147], v[140:141], 0, s[98:99]
	global_load_dwordx2 v[168:169], v[146:147], off
	s_mov_b32 s98, 0x23a02800
	v_lshl_add_u64 v[144:145], v[140:141], 0, s[98:99]
	global_load_dwordx2 v[170:171], v[144:145], off offset:-2048
	global_load_dwordx2 v[172:173], v[144:145], off offset:2048
	global_load_dwordx2 v[174:175], v[148:149], off offset:2048
	s_mov_b32 s98, 0x1ba03000
	v_lshl_add_u64 v[146:147], v[140:141], 0, s[98:99]
	global_load_dwordx2 v[176:177], v[146:147], off
	s_mov_b32 s98, 0x23a04800
	v_lshl_add_u64 v[144:145], v[140:141], 0, s[98:99]
	global_load_dwordx2 v[178:179], v[144:145], off offset:-2048
	global_load_dwordx2 v[182:183], v[144:145], off offset:2048
	s_mov_b32 s98, 0x1fa02800
	v_lshl_add_u64 v[148:149], v[142:143], 0, s[98:99]
	global_load_dwordx2 v[184:185], v[148:149], off offset:-2048
	s_mov_b32 s98, 0x1ba05000
	v_lshl_add_u64 v[146:147], v[140:141], 0, s[98:99]
	global_load_dwordx2 v[186:187], v[146:147], off
	s_mov_b32 s98, 0x23a06800
	v_lshl_add_u64 v[144:145], v[140:141], 0, s[98:99]
	global_load_dwordx2 v[190:191], v[144:145], off offset:-2048
	global_load_dwordx2 v[194:195], v[144:145], off offset:2048
	global_load_dwordx2 v[196:197], v[148:149], off offset:2048
	s_mov_b32 s98, 0x1ba07000
	v_lshl_add_u64 v[146:147], v[140:141], 0, s[98:99]
	global_load_dwordx2 v[198:199], v[146:147], off
	s_mov_b32 s98, 0x23a08800
	v_lshl_add_u64 v[144:145], v[140:141], 0, s[98:99]
	global_load_dwordx2 v[200:201], v[144:145], off offset:-2048
	global_load_dwordx2 v[202:203], v[144:145], off offset:2048
	s_mov_b32 s98, 0x1fa04800
	v_lshl_add_u64 v[148:149], v[142:143], 0, s[98:99]
	global_load_dwordx2 v[204:205], v[148:149], off offset:-2048
	s_mov_b32 s98, 0x1ba09000
	v_lshl_add_u64 v[146:147], v[140:141], 0, s[98:99]
	global_load_dwordx2 v[206:207], v[146:147], off
	s_mov_b32 s98, 0x23a0a800
	v_lshl_add_u64 v[144:145], v[140:141], 0, s[98:99]
	global_load_dwordx2 v[208:209], v[144:145], off offset:-2048
	global_load_dwordx2 v[210:211], v[144:145], off offset:2048
	global_load_dwordx2 v[212:213], v[148:149], off offset:2048
	s_mov_b32 s98, 0x1ba0b000
	v_lshl_add_u64 v[146:147], v[140:141], 0, s[98:99]
	global_load_dwordx2 v[214:215], v[146:147], off
	s_mov_b32 s98, 0x23a0c800
	v_lshl_add_u64 v[144:145], v[140:141], 0, s[98:99]
	global_load_dwordx2 v[216:217], v[144:145], off offset:-2048
	global_load_dwordx2 v[218:219], v[144:145], off offset:2048
	s_mov_b32 s98, 0x1fa06800
	v_lshl_add_u64 v[148:149], v[142:143], 0, s[98:99]
	global_load_dwordx2 v[222:223], v[148:149], off offset:-2048
	s_mov_b32 s98, 0x1ba0d000
	v_lshl_add_u64 v[146:147], v[140:141], 0, s[98:99]
	global_load_dwordx2 v[224:225], v[146:147], off
	s_mov_b32 s98, 0x23a0e800
	v_lshl_add_u64 v[144:145], v[140:141], 0, s[98:99]
	global_load_dwordx2 v[226:227], v[144:145], off offset:-2048
	global_load_dwordx2 v[232:233], v[144:145], off offset:2048
	global_load_dwordx2 v[234:235], v[148:149], off offset:2048
	s_mov_b32 s98, 0x1ba0f000
	v_lshl_add_u64 v[146:147], v[140:141], 0, s[98:99]
	global_load_dwordx2 v[238:239], v[146:147], off
	v_add_co_u32_e32 v148, vcc, 0x1fa00000, v142
	v_lshl_add_u64 v[132:133], v[132:133], 0, s[6:7]
	s_nop 0
	v_addc_co_u32_e32 v149, vcc, 0, v143, vcc
	s_mov_b64 s[6:7], 0x10000
	s_add_i32 s0, s0, -8
	v_lshl_add_u64 v[134:135], v[134:135], 0, s[6:7]
	s_cmp_eq_u32 s0, 0
	s_waitcnt vmcnt(28)
	v_lshlrev_b32_e32 v150, 16, v162
	v_and_b32_e32 v151, 0xffff0000, v162
	v_lshlrev_b32_e32 v154, 16, v163
	v_and_b32_e32 v155, 0xffff0000, v163
	v_lshlrev_b32_e32 v144, 16, v164
	v_and_b32_e32 v145, 0xffff0000, v164
	v_add_f32_e32 v146, v68, v150
	v_mul_f32_e32 v146, 0xbfb8aa3b, v146
	v_exp_f32_e32 v146, v146
	v_lshlrev_b32_e32 v156, 16, v165
	v_and_b32_e32 v157, 0xffff0000, v165
	v_add_f32_e32 v144, v64, v144
	v_add_f32_e32 v146, 1.0, v146
	v_rcp_f32_e32 v146, v146
	v_add_f32_e32 v145, v65, v145
	v_mul_f32_e32 v144, 0xbfb8aa3b, v144
	v_mul_f32_e32 v145, 0xbfb8aa3b, v145
	v_mul_f32_e32 v146, v72, v146
	v_exp_f32_e32 v146, v146
	v_exp_f32_e32 v144, v144
	v_exp_f32_e32 v145, v145
	v_and_b32_e32 v153, 0xffff0000, v166
	v_sub_f32_e32 v147, 1.0, v146
	v_add_f32_e32 v150, 1.0, v146
	v_mul_f32_e32 v147, v147, v150
	v_sqrt_f32_e32 v150, v147
	v_add_f32_e32 v147, v69, v151
	v_mul_f32_e32 v147, 0xbfb8aa3b, v147
	v_exp_f32_e32 v147, v147
	v_add_f32_e32 v144, 1.0, v144
	v_add_f32_e32 v145, 1.0, v145
	v_rcp_f32_e32 v144, v144
	v_add_f32_e32 v147, 1.0, v147
	v_rcp_f32_e32 v147, v147
	v_rcp_f32_e32 v145, v145
	v_mul_f32_e32 v147, v73, v147
	v_exp_f32_e32 v147, v147
	s_nop 0
	v_sub_f32_e32 v151, 1.0, v147
	v_add_f32_e32 v152, 1.0, v147
	v_mul_f32_e32 v151, v151, v152
	v_sqrt_f32_e32 v151, v151
	v_lshlrev_b32_e32 v152, 16, v166
	v_pk_mul_f32 v[144:145], v[144:145], v[152:153]
	v_add_f32_e32 v148, v70, v154
	v_pk_mul_f32 v[144:145], v[144:145], v[150:151]
	v_mul_f32_e32 v148, 0xbfb8aa3b, v148
	v_pk_fma_f32 v[138:139], v[138:139], v[146:147], v[144:145]
	v_add_co_u32_e32 v144, vcc, s1, v140
	v_exp_f32_e32 v148, v148
	s_nop 0
	v_addc_co_u32_e32 v145, vcc, 0, v141, vcc
	v_add_f32_e32 v148, 1.0, v148
	v_rcp_f32_e32 v148, v148
	v_add_f32_e32 v150, v66, v156
	v_mul_f32_e32 v150, 0xbfb8aa3b, v150
	v_exp_f32_e32 v150, v150
	v_mul_f32_e32 v148, v74, v148
	v_exp_f32_e32 v152, v148
	s_mov_b32 s1, 0x21a01000
	v_add_f32_e32 v150, 1.0, v150
	v_rcp_f32_e32 v150, v150
	v_sub_f32_e32 v148, 1.0, v152
	v_add_f32_e32 v151, 1.0, v152
	v_mul_f32_e32 v148, v148, v151
	v_sqrt_f32_e32 v154, v148
	v_add_f32_e32 v148, v71, v155
	v_mul_f32_e32 v148, 0xbfb8aa3b, v148
	v_exp_f32_e32 v148, v148
	v_add_f32_e32 v151, v67, v157
	v_mul_f32_e32 v151, 0xbfb8aa3b, v151
	v_exp_f32_e32 v151, v151
	v_add_f32_e32 v148, 1.0, v148
	v_rcp_f32_e32 v148, v148
	v_add_f32_e32 v151, 1.0, v151
	v_rcp_f32_e32 v151, v151
	v_mul_f32_e32 v148, v75, v148
	v_exp_f32_e32 v153, v148
	v_lshlrev_b32_e32 v146, 16, v168
	v_sub_f32_e32 v148, 1.0, v153
	v_add_f32_e32 v155, 1.0, v153
	v_mul_f32_e32 v148, v148, v155
	v_sqrt_f32_e32 v155, v148
	v_lshlrev_b32_e32 v148, 16, v167
	v_and_b32_e32 v149, 0xffff0000, v167
	v_pk_mul_f32 v[148:149], v[150:151], v[148:149]
	v_and_b32_e32 v147, 0xffff0000, v168
	v_pk_mul_f32 v[148:149], v[148:149], v[154:155]
	v_pk_mul_f32 v[146:147], v[138:139], v[146:147]
	v_pk_fma_f32 v[136:137], v[136:137], v[152:153], v[148:149]
	v_cvt_pk_bf16_f32 v144, v146, v147
	v_lshlrev_b32_e32 v146, 16, v169
	v_and_b32_e32 v147, 0xffff0000, v169
	v_pk_mul_f32 v[146:147], v[136:137], v[146:147]
	s_nop 0
	v_cvt_pk_bf16_f32 v145, v146, v147
	v_add_co_u32_e32 v146, vcc, s1, v142
	s_mov_b32 s1, 0x23a03000
	s_nop 0
	v_addc_co_u32_e32 v147, vcc, 0, v143, vcc
	global_store_dwordx2 v[146:147], v[144:145], off offset:-4096
	v_add_co_u32_e32 v144, vcc, s1, v140
	s_mov_b32 s1, 0x1fa02000
	s_nop 0
	v_addc_co_u32_e32 v145, vcc, 0, v141, vcc
	s_nop 0
	v_add_co_u32_e32 v150, vcc, s1, v142
	s_mov_b32 s1, 0x1ba03000
	s_nop 0
	v_addc_co_u32_e32 v151, vcc, 0, v143, vcc
	s_waitcnt vmcnt(25)
	v_lshlrev_b32_e32 v154, 16, v170
	v_and_b32_e32 v155, 0xffff0000, v170
	v_lshlrev_b32_e32 v158, 16, v171
	v_and_b32_e32 v159, 0xffff0000, v171
	v_lshlrev_b32_e32 v148, 16, v172
	v_and_b32_e32 v149, 0xffff0000, v172
	v_add_f32_e32 v144, v68, v154
	v_mul_f32_e32 v144, 0xbfb8aa3b, v144
	v_exp_f32_e32 v144, v144
	v_lshlrev_b32_e32 v160, 16, v173
	v_and_b32_e32 v161, 0xffff0000, v173
	v_and_b32_e32 v157, 0xffff0000, v174
	v_add_f32_e32 v144, 1.0, v144
	v_rcp_f32_e32 v145, v144
	v_add_f32_e32 v144, v64, v148
	v_mul_f32_e32 v144, 0xbfb8aa3b, v144
	v_exp_f32_e32 v144, v144
	v_mul_f32_e32 v145, v72, v145
	v_exp_f32_e32 v148, v145
	v_add_f32_e32 v144, 1.0, v144
	v_rcp_f32_e32 v144, v144
	v_sub_f32_e32 v145, 1.0, v148
	v_add_f32_e32 v154, 1.0, v148
	v_mul_f32_e32 v145, v145, v154
	v_sqrt_f32_e32 v154, v145
	v_add_f32_e32 v145, v69, v155
	v_mul_f32_e32 v145, 0xbfb8aa3b, v145
	v_exp_f32_e32 v145, v145
	s_nop 0
	v_add_f32_e32 v145, 1.0, v145
	v_rcp_f32_e32 v155, v145
	v_add_f32_e32 v145, v65, v149
	v_mul_f32_e32 v145, 0xbfb8aa3b, v145
	v_exp_f32_e32 v145, v145
	v_mul_f32_e32 v149, v73, v155
	v_exp_f32_e32 v149, v149
	v_add_f32_e32 v145, 1.0, v145
	v_rcp_f32_e32 v145, v145
	v_sub_f32_e32 v155, 1.0, v149
	v_add_f32_e32 v156, 1.0, v149
	v_mul_f32_e32 v155, v155, v156
	v_sqrt_f32_e32 v155, v155
	v_lshlrev_b32_e32 v156, 16, v174
	v_pk_mul_f32 v[144:145], v[144:145], v[156:157]
	v_add_f32_e32 v152, v70, v158
	v_pk_mul_f32 v[144:145], v[144:145], v[154:155]
	v_mul_f32_e32 v152, 0xbfb8aa3b, v152
	v_pk_fma_f32 v[138:139], v[138:139], v[148:149], v[144:145]
	v_add_co_u32_e32 v144, vcc, s1, v140
	v_exp_f32_e32 v152, v152
	s_nop 0
	v_addc_co_u32_e32 v145, vcc, 0, v141, vcc
	v_add_f32_e32 v152, 1.0, v152
	v_rcp_f32_e32 v152, v152
	v_add_f32_e32 v154, v66, v160
	v_mul_f32_e32 v154, 0xbfb8aa3b, v154
	v_exp_f32_e32 v154, v154
	v_mul_f32_e32 v152, v74, v152
	v_exp_f32_e32 v156, v152
	s_mov_b32 s1, 0x23a05000
	v_add_f32_e32 v154, 1.0, v154
	v_rcp_f32_e32 v154, v154
	v_sub_f32_e32 v152, 1.0, v156
	v_add_f32_e32 v155, 1.0, v156
	v_mul_f32_e32 v152, v152, v155
	v_sqrt_f32_e32 v158, v152
	v_add_f32_e32 v152, v71, v159
	v_mul_f32_e32 v152, 0xbfb8aa3b, v152
	v_exp_f32_e32 v152, v152
	v_add_f32_e32 v155, v67, v161
	v_mul_f32_e32 v155, 0xbfb8aa3b, v155
	v_exp_f32_e32 v155, v155
	v_add_f32_e32 v152, 1.0, v152
	v_rcp_f32_e32 v152, v152
	v_add_f32_e32 v155, 1.0, v155
	v_rcp_f32_e32 v155, v155
	v_mul_f32_e32 v152, v75, v152
	v_exp_f32_e32 v157, v152
	v_lshlrev_b32_e32 v148, 16, v176
	v_sub_f32_e32 v152, 1.0, v157
	v_add_f32_e32 v159, 1.0, v157
	v_mul_f32_e32 v152, v152, v159
	v_sqrt_f32_e32 v159, v152
	v_lshlrev_b32_e32 v152, 16, v175
	v_and_b32_e32 v153, 0xffff0000, v175
	v_pk_mul_f32 v[152:153], v[154:155], v[152:153]
	v_and_b32_e32 v149, 0xffff0000, v176
	v_pk_mul_f32 v[152:153], v[152:153], v[158:159]
	v_pk_mul_f32 v[148:149], v[138:139], v[148:149]
	v_pk_fma_f32 v[136:137], v[136:137], v[156:157], v[152:153]
	v_cvt_pk_bf16_f32 v144, v148, v149
	v_lshlrev_b32_e32 v148, 16, v177
	v_and_b32_e32 v149, 0xffff0000, v177
	v_pk_mul_f32 v[148:149], v[136:137], v[148:149]
	s_nop 0
	v_cvt_pk_bf16_f32 v145, v148, v149
	global_store_dwordx2 v[146:147], v[144:145], off
	v_add_co_u32_e32 v144, vcc, s1, v140
	s_mov_b32 s1, 0x1ba05000
	s_nop 0
	v_addc_co_u32_e32 v145, vcc, 0, v141, vcc
	s_nop 0
	s_nop 0
	s_waitcnt vmcnt(22)
	v_lshlrev_b32_e32 v150, 16, v178
	v_and_b32_e32 v151, 0xffff0000, v178
	v_lshlrev_b32_e32 v154, 16, v179
	v_and_b32_e32 v155, 0xffff0000, v179
	v_lshlrev_b32_e32 v146, 16, v182
	v_and_b32_e32 v147, 0xffff0000, v182
	v_add_f32_e32 v144, v68, v150
	v_mul_f32_e32 v144, 0xbfb8aa3b, v144
	v_exp_f32_e32 v144, v144
	v_lshlrev_b32_e32 v156, 16, v183
	v_and_b32_e32 v157, 0xffff0000, v183
	v_and_b32_e32 v153, 0xffff0000, v184
	v_add_f32_e32 v144, 1.0, v144
	v_rcp_f32_e32 v145, v144
	v_add_f32_e32 v144, v64, v146
	v_mul_f32_e32 v144, 0xbfb8aa3b, v144
	v_exp_f32_e32 v144, v144
	v_mul_f32_e32 v145, v72, v145
	v_exp_f32_e32 v146, v145
	v_add_f32_e32 v144, 1.0, v144
	v_rcp_f32_e32 v144, v144
	v_sub_f32_e32 v145, 1.0, v146
	v_add_f32_e32 v150, 1.0, v146
	v_mul_f32_e32 v145, v145, v150
	v_sqrt_f32_e32 v150, v145
	v_add_f32_e32 v145, v69, v151
	v_mul_f32_e32 v145, 0xbfb8aa3b, v145
	v_exp_f32_e32 v145, v145
	s_nop 0
	v_add_f32_e32 v145, 1.0, v145
	v_rcp_f32_e32 v151, v145
	v_add_f32_e32 v145, v65, v147
	v_mul_f32_e32 v145, 0xbfb8aa3b, v145
	v_exp_f32_e32 v145, v145
	v_mul_f32_e32 v147, v73, v151
	v_exp_f32_e32 v147, v147
	v_add_f32_e32 v145, 1.0, v145
	v_rcp_f32_e32 v145, v145
	v_sub_f32_e32 v151, 1.0, v147
	v_add_f32_e32 v152, 1.0, v147
	v_mul_f32_e32 v151, v151, v152
	v_sqrt_f32_e32 v151, v151
	v_lshlrev_b32_e32 v152, 16, v184
	v_pk_mul_f32 v[144:145], v[144:145], v[152:153]
	v_add_f32_e32 v148, v70, v154
	v_pk_mul_f32 v[144:145], v[144:145], v[150:151]
	v_mul_f32_e32 v148, 0xbfb8aa3b, v148
	v_pk_fma_f32 v[138:139], v[138:139], v[146:147], v[144:145]
	v_add_co_u32_e32 v144, vcc, s1, v140
	v_exp_f32_e32 v148, v148
	s_nop 0
	v_addc_co_u32_e32 v145, vcc, 0, v141, vcc
	v_add_f32_e32 v148, 1.0, v148
	v_rcp_f32_e32 v148, v148
	v_add_f32_e32 v150, v66, v156
	v_mul_f32_e32 v150, 0xbfb8aa3b, v150
	v_exp_f32_e32 v150, v150
	v_mul_f32_e32 v148, v74, v148
	v_exp_f32_e32 v152, v148
	s_mov_b32 s1, 0x21a03000
	v_add_f32_e32 v150, 1.0, v150
	v_rcp_f32_e32 v150, v150
	v_sub_f32_e32 v148, 1.0, v152
	v_add_f32_e32 v151, 1.0, v152
	v_mul_f32_e32 v148, v148, v151
	v_sqrt_f32_e32 v154, v148
	v_add_f32_e32 v148, v71, v155
	v_mul_f32_e32 v148, 0xbfb8aa3b, v148
	v_exp_f32_e32 v148, v148
	v_add_f32_e32 v151, v67, v157
	v_mul_f32_e32 v151, 0xbfb8aa3b, v151
	v_exp_f32_e32 v151, v151
	v_add_f32_e32 v148, 1.0, v148
	v_rcp_f32_e32 v148, v148
	v_add_f32_e32 v151, 1.0, v151
	v_rcp_f32_e32 v151, v151
	v_mul_f32_e32 v148, v75, v148
	v_exp_f32_e32 v153, v148
	v_lshlrev_b32_e32 v146, 16, v186
	v_sub_f32_e32 v148, 1.0, v153
	v_add_f32_e32 v155, 1.0, v153
	v_mul_f32_e32 v148, v148, v155
	v_sqrt_f32_e32 v155, v148
	v_lshlrev_b32_e32 v148, 16, v185
	v_and_b32_e32 v149, 0xffff0000, v185
	v_pk_mul_f32 v[148:149], v[150:151], v[148:149]
	v_and_b32_e32 v147, 0xffff0000, v186
	v_pk_mul_f32 v[148:149], v[148:149], v[154:155]
	v_pk_mul_f32 v[146:147], v[138:139], v[146:147]
	v_pk_fma_f32 v[136:137], v[136:137], v[152:153], v[148:149]
	v_cvt_pk_bf16_f32 v144, v146, v147
	v_lshlrev_b32_e32 v146, 16, v187
	v_and_b32_e32 v147, 0xffff0000, v187
	v_pk_mul_f32 v[146:147], v[136:137], v[146:147]
	s_nop 0
	v_cvt_pk_bf16_f32 v145, v146, v147
	v_add_co_u32_e32 v146, vcc, s1, v142
	s_mov_b32 s1, 0x23a07000
	s_nop 0
	v_addc_co_u32_e32 v147, vcc, 0, v143, vcc
	global_store_dwordx2 v[146:147], v[144:145], off offset:-4096
	v_add_co_u32_e32 v144, vcc, s1, v140
	s_mov_b32 s1, 0x1fa04000
	s_nop 0
	v_addc_co_u32_e32 v145, vcc, 0, v141, vcc
	s_nop 0
	v_add_co_u32_e32 v150, vcc, s1, v142
	s_mov_b32 s1, 0x1ba07000
	s_nop 0
	v_addc_co_u32_e32 v151, vcc, 0, v143, vcc
	s_waitcnt vmcnt(19)
	v_lshlrev_b32_e32 v154, 16, v190
	v_and_b32_e32 v155, 0xffff0000, v190
	v_lshlrev_b32_e32 v158, 16, v191
	v_and_b32_e32 v159, 0xffff0000, v191
	v_lshlrev_b32_e32 v148, 16, v194
	v_and_b32_e32 v149, 0xffff0000, v194
	v_add_f32_e32 v144, v68, v154
	v_mul_f32_e32 v144, 0xbfb8aa3b, v144
	v_exp_f32_e32 v144, v144
	v_lshlrev_b32_e32 v160, 16, v195
	v_and_b32_e32 v161, 0xffff0000, v195
	v_and_b32_e32 v157, 0xffff0000, v196
	v_add_f32_e32 v144, 1.0, v144
	v_rcp_f32_e32 v145, v144
	v_add_f32_e32 v144, v64, v148
	v_mul_f32_e32 v144, 0xbfb8aa3b, v144
	v_exp_f32_e32 v144, v144
	v_mul_f32_e32 v145, v72, v145
	v_exp_f32_e32 v148, v145
	v_add_f32_e32 v144, 1.0, v144
	v_rcp_f32_e32 v144, v144
	v_sub_f32_e32 v145, 1.0, v148
	v_add_f32_e32 v154, 1.0, v148
	v_mul_f32_e32 v145, v145, v154
	v_sqrt_f32_e32 v154, v145
	v_add_f32_e32 v145, v69, v155
	v_mul_f32_e32 v145, 0xbfb8aa3b, v145
	v_exp_f32_e32 v145, v145
	s_nop 0
	v_add_f32_e32 v145, 1.0, v145
	v_rcp_f32_e32 v155, v145
	v_add_f32_e32 v145, v65, v149
	v_mul_f32_e32 v145, 0xbfb8aa3b, v145
	v_exp_f32_e32 v145, v145
	v_mul_f32_e32 v149, v73, v155
	v_exp_f32_e32 v149, v149
	v_add_f32_e32 v145, 1.0, v145
	v_rcp_f32_e32 v145, v145
	v_sub_f32_e32 v155, 1.0, v149
	v_add_f32_e32 v156, 1.0, v149
	v_mul_f32_e32 v155, v155, v156
	v_sqrt_f32_e32 v155, v155
	v_lshlrev_b32_e32 v156, 16, v196
	v_pk_mul_f32 v[144:145], v[144:145], v[156:157]
	v_add_f32_e32 v152, v70, v158
	v_pk_mul_f32 v[144:145], v[144:145], v[154:155]
	v_mul_f32_e32 v152, 0xbfb8aa3b, v152
	v_pk_fma_f32 v[138:139], v[138:139], v[148:149], v[144:145]
	v_add_co_u32_e32 v144, vcc, s1, v140
	v_exp_f32_e32 v152, v152
	s_nop 0
	v_addc_co_u32_e32 v145, vcc, 0, v141, vcc
	v_add_f32_e32 v152, 1.0, v152
	v_rcp_f32_e32 v152, v152
	v_add_f32_e32 v154, v66, v160
	v_mul_f32_e32 v154, 0xbfb8aa3b, v154
	v_exp_f32_e32 v154, v154
	v_mul_f32_e32 v152, v74, v152
	v_exp_f32_e32 v156, v152
	s_mov_b32 s1, 0x23a09000
	v_add_f32_e32 v154, 1.0, v154
	v_rcp_f32_e32 v154, v154
	v_sub_f32_e32 v152, 1.0, v156
	v_add_f32_e32 v155, 1.0, v156
	v_mul_f32_e32 v152, v152, v155
	v_sqrt_f32_e32 v158, v152
	v_add_f32_e32 v152, v71, v159
	v_mul_f32_e32 v152, 0xbfb8aa3b, v152
	v_exp_f32_e32 v152, v152
	v_add_f32_e32 v155, v67, v161
	v_mul_f32_e32 v155, 0xbfb8aa3b, v155
	v_exp_f32_e32 v155, v155
	v_add_f32_e32 v152, 1.0, v152
	v_rcp_f32_e32 v152, v152
	v_add_f32_e32 v155, 1.0, v155
	v_rcp_f32_e32 v155, v155
	v_mul_f32_e32 v152, v75, v152
	v_exp_f32_e32 v157, v152
	v_lshlrev_b32_e32 v148, 16, v198
	v_sub_f32_e32 v152, 1.0, v157
	v_add_f32_e32 v159, 1.0, v157
	v_mul_f32_e32 v152, v152, v159
	v_sqrt_f32_e32 v159, v152
	v_lshlrev_b32_e32 v152, 16, v197
	v_and_b32_e32 v153, 0xffff0000, v197
	v_pk_mul_f32 v[152:153], v[154:155], v[152:153]
	v_and_b32_e32 v149, 0xffff0000, v198
	v_pk_mul_f32 v[152:153], v[152:153], v[158:159]
	v_pk_mul_f32 v[148:149], v[138:139], v[148:149]
	v_pk_fma_f32 v[136:137], v[136:137], v[156:157], v[152:153]
	v_cvt_pk_bf16_f32 v144, v148, v149
	v_lshlrev_b32_e32 v148, 16, v199
	v_and_b32_e32 v149, 0xffff0000, v199
	v_pk_mul_f32 v[148:149], v[136:137], v[148:149]
	s_nop 0
	v_cvt_pk_bf16_f32 v145, v148, v149
	global_store_dwordx2 v[146:147], v[144:145], off
	v_add_co_u32_e32 v144, vcc, s1, v140
	s_mov_b32 s1, 0x1ba09000
	s_nop 0
	v_addc_co_u32_e32 v145, vcc, 0, v141, vcc
	s_nop 0
	s_nop 0
	s_waitcnt vmcnt(16)
	v_lshlrev_b32_e32 v150, 16, v200
	v_and_b32_e32 v151, 0xffff0000, v200
	v_lshlrev_b32_e32 v154, 16, v201
	v_and_b32_e32 v155, 0xffff0000, v201
	v_lshlrev_b32_e32 v146, 16, v202
	v_and_b32_e32 v147, 0xffff0000, v202
	v_add_f32_e32 v144, v68, v150
	v_mul_f32_e32 v144, 0xbfb8aa3b, v144
	v_exp_f32_e32 v144, v144
	v_lshlrev_b32_e32 v156, 16, v203
	v_and_b32_e32 v157, 0xffff0000, v203
	v_and_b32_e32 v153, 0xffff0000, v204
	v_add_f32_e32 v144, 1.0, v144
	v_rcp_f32_e32 v145, v144
	v_add_f32_e32 v144, v64, v146
	v_mul_f32_e32 v144, 0xbfb8aa3b, v144
	v_exp_f32_e32 v144, v144
	v_mul_f32_e32 v145, v72, v145
	v_exp_f32_e32 v146, v145
	v_add_f32_e32 v144, 1.0, v144
	v_rcp_f32_e32 v144, v144
	v_sub_f32_e32 v145, 1.0, v146
	v_add_f32_e32 v150, 1.0, v146
	v_mul_f32_e32 v145, v145, v150
	v_sqrt_f32_e32 v150, v145
	v_add_f32_e32 v145, v69, v151
	v_mul_f32_e32 v145, 0xbfb8aa3b, v145
	v_exp_f32_e32 v145, v145
	s_nop 0
	v_add_f32_e32 v145, 1.0, v145
	v_rcp_f32_e32 v151, v145
	v_add_f32_e32 v145, v65, v147
	v_mul_f32_e32 v145, 0xbfb8aa3b, v145
	v_exp_f32_e32 v145, v145
	v_mul_f32_e32 v147, v73, v151
	v_exp_f32_e32 v147, v147
	v_add_f32_e32 v145, 1.0, v145
	v_rcp_f32_e32 v145, v145
	v_sub_f32_e32 v151, 1.0, v147
	v_add_f32_e32 v152, 1.0, v147
	v_mul_f32_e32 v151, v151, v152
	v_sqrt_f32_e32 v151, v151
	v_lshlrev_b32_e32 v152, 16, v204
	v_pk_mul_f32 v[144:145], v[144:145], v[152:153]
	v_add_f32_e32 v148, v70, v154
	v_pk_mul_f32 v[144:145], v[144:145], v[150:151]
	v_mul_f32_e32 v148, 0xbfb8aa3b, v148
	v_pk_fma_f32 v[138:139], v[138:139], v[146:147], v[144:145]
	v_add_co_u32_e32 v144, vcc, s1, v140
	v_exp_f32_e32 v148, v148
	s_nop 0
	v_addc_co_u32_e32 v145, vcc, 0, v141, vcc
	v_add_f32_e32 v148, 1.0, v148
	v_rcp_f32_e32 v148, v148
	v_add_f32_e32 v150, v66, v156
	v_mul_f32_e32 v150, 0xbfb8aa3b, v150
	v_exp_f32_e32 v150, v150
	v_mul_f32_e32 v148, v74, v148
	v_exp_f32_e32 v152, v148
	s_mov_b32 s1, 0x21a05000
	v_add_f32_e32 v150, 1.0, v150
	v_rcp_f32_e32 v150, v150
	v_sub_f32_e32 v148, 1.0, v152
	v_add_f32_e32 v151, 1.0, v152
	v_mul_f32_e32 v148, v148, v151
	v_sqrt_f32_e32 v154, v148
	v_add_f32_e32 v148, v71, v155
	v_mul_f32_e32 v148, 0xbfb8aa3b, v148
	v_exp_f32_e32 v148, v148
	v_add_f32_e32 v151, v67, v157
	v_mul_f32_e32 v151, 0xbfb8aa3b, v151
	v_exp_f32_e32 v151, v151
	v_add_f32_e32 v148, 1.0, v148
	v_rcp_f32_e32 v148, v148
	v_add_f32_e32 v151, 1.0, v151
	v_rcp_f32_e32 v151, v151
	v_mul_f32_e32 v148, v75, v148
	v_exp_f32_e32 v153, v148
	v_lshlrev_b32_e32 v146, 16, v206
	v_sub_f32_e32 v148, 1.0, v153
	v_add_f32_e32 v155, 1.0, v153
	v_mul_f32_e32 v148, v148, v155
	v_sqrt_f32_e32 v155, v148
	v_lshlrev_b32_e32 v148, 16, v205
	v_and_b32_e32 v149, 0xffff0000, v205
	v_pk_mul_f32 v[148:149], v[150:151], v[148:149]
	v_and_b32_e32 v147, 0xffff0000, v206
	v_pk_mul_f32 v[148:149], v[148:149], v[154:155]
	v_pk_mul_f32 v[146:147], v[138:139], v[146:147]
	v_pk_fma_f32 v[136:137], v[136:137], v[152:153], v[148:149]
	v_cvt_pk_bf16_f32 v144, v146, v147
	v_lshlrev_b32_e32 v146, 16, v207
	v_and_b32_e32 v147, 0xffff0000, v207
	v_pk_mul_f32 v[146:147], v[136:137], v[146:147]
	s_nop 0
	v_cvt_pk_bf16_f32 v145, v146, v147
	v_add_co_u32_e32 v146, vcc, s1, v142
	s_mov_b32 s1, 0x23a0b000
	s_nop 0
	v_addc_co_u32_e32 v147, vcc, 0, v143, vcc
	global_store_dwordx2 v[146:147], v[144:145], off offset:-4096
	v_add_co_u32_e32 v144, vcc, s1, v140
	s_mov_b32 s1, 0x1fa06000
	s_nop 0
	v_addc_co_u32_e32 v145, vcc, 0, v141, vcc
	s_nop 0
	v_add_co_u32_e32 v150, vcc, s1, v142
	s_mov_b32 s1, 0x1ba0b000
	s_nop 0
	v_addc_co_u32_e32 v151, vcc, 0, v143, vcc
	s_waitcnt vmcnt(13)
	v_lshlrev_b32_e32 v154, 16, v208
	v_and_b32_e32 v155, 0xffff0000, v208
	v_lshlrev_b32_e32 v158, 16, v209
	v_and_b32_e32 v159, 0xffff0000, v209
	v_lshlrev_b32_e32 v148, 16, v210
	v_and_b32_e32 v149, 0xffff0000, v210
	v_add_f32_e32 v144, v68, v154
	v_mul_f32_e32 v144, 0xbfb8aa3b, v144
	v_exp_f32_e32 v144, v144
	v_lshlrev_b32_e32 v160, 16, v211
	v_and_b32_e32 v161, 0xffff0000, v211
	v_and_b32_e32 v157, 0xffff0000, v212
	v_add_f32_e32 v144, 1.0, v144
	v_rcp_f32_e32 v145, v144
	v_add_f32_e32 v144, v64, v148
	v_mul_f32_e32 v144, 0xbfb8aa3b, v144
	v_exp_f32_e32 v144, v144
	v_mul_f32_e32 v145, v72, v145
	v_exp_f32_e32 v148, v145
	v_add_f32_e32 v144, 1.0, v144
	v_rcp_f32_e32 v144, v144
	v_sub_f32_e32 v145, 1.0, v148
	v_add_f32_e32 v154, 1.0, v148
	v_mul_f32_e32 v145, v145, v154
	v_sqrt_f32_e32 v154, v145
	v_add_f32_e32 v145, v69, v155
	v_mul_f32_e32 v145, 0xbfb8aa3b, v145
	v_exp_f32_e32 v145, v145
	s_nop 0
	v_add_f32_e32 v145, 1.0, v145
	v_rcp_f32_e32 v155, v145
	v_add_f32_e32 v145, v65, v149
	v_mul_f32_e32 v145, 0xbfb8aa3b, v145
	v_exp_f32_e32 v145, v145
	v_mul_f32_e32 v149, v73, v155
	v_exp_f32_e32 v149, v149
	v_add_f32_e32 v145, 1.0, v145
	v_rcp_f32_e32 v145, v145
	v_sub_f32_e32 v155, 1.0, v149
	v_add_f32_e32 v156, 1.0, v149
	v_mul_f32_e32 v155, v155, v156
	v_sqrt_f32_e32 v155, v155
	v_lshlrev_b32_e32 v156, 16, v212
	v_pk_mul_f32 v[144:145], v[144:145], v[156:157]
	v_add_f32_e32 v152, v70, v158
	v_pk_mul_f32 v[144:145], v[144:145], v[154:155]
	v_mul_f32_e32 v152, 0xbfb8aa3b, v152
	v_pk_fma_f32 v[138:139], v[138:139], v[148:149], v[144:145]
	v_add_co_u32_e32 v144, vcc, s1, v140
	v_exp_f32_e32 v152, v152
	s_nop 0
	v_addc_co_u32_e32 v145, vcc, 0, v141, vcc
	v_add_f32_e32 v152, 1.0, v152
	v_rcp_f32_e32 v152, v152
	v_add_f32_e32 v154, v66, v160
	v_mul_f32_e32 v154, 0xbfb8aa3b, v154
	v_exp_f32_e32 v154, v154
	v_mul_f32_e32 v152, v74, v152
	v_exp_f32_e32 v156, v152
	s_mov_b32 s1, 0x23a0d000
	v_add_f32_e32 v154, 1.0, v154
	v_rcp_f32_e32 v154, v154
	v_sub_f32_e32 v152, 1.0, v156
	v_add_f32_e32 v155, 1.0, v156
	v_mul_f32_e32 v152, v152, v155
	v_sqrt_f32_e32 v158, v152
	v_add_f32_e32 v152, v71, v159
	v_mul_f32_e32 v152, 0xbfb8aa3b, v152
	v_exp_f32_e32 v152, v152
	v_add_f32_e32 v155, v67, v161
	v_mul_f32_e32 v155, 0xbfb8aa3b, v155
	v_exp_f32_e32 v155, v155
	v_add_f32_e32 v152, 1.0, v152
	v_rcp_f32_e32 v152, v152
	v_add_f32_e32 v155, 1.0, v155
	v_rcp_f32_e32 v155, v155
	v_mul_f32_e32 v152, v75, v152
	v_exp_f32_e32 v157, v152
	v_lshlrev_b32_e32 v148, 16, v214
	v_sub_f32_e32 v152, 1.0, v157
	v_add_f32_e32 v159, 1.0, v157
	v_mul_f32_e32 v152, v152, v159
	v_sqrt_f32_e32 v159, v152
	v_lshlrev_b32_e32 v152, 16, v213
	v_and_b32_e32 v153, 0xffff0000, v213
	v_pk_mul_f32 v[152:153], v[154:155], v[152:153]
	v_and_b32_e32 v149, 0xffff0000, v214
	v_pk_mul_f32 v[152:153], v[152:153], v[158:159]
	v_pk_mul_f32 v[148:149], v[138:139], v[148:149]
	v_pk_fma_f32 v[136:137], v[136:137], v[156:157], v[152:153]
	v_cvt_pk_bf16_f32 v144, v148, v149
	v_lshlrev_b32_e32 v148, 16, v215
	v_and_b32_e32 v149, 0xffff0000, v215
	v_pk_mul_f32 v[148:149], v[136:137], v[148:149]
	s_nop 0
	v_cvt_pk_bf16_f32 v145, v148, v149
	global_store_dwordx2 v[146:147], v[144:145], off
	v_add_co_u32_e32 v144, vcc, s1, v140
	s_mov_b32 s1, 0x1ba0d000
	s_nop 0
	v_addc_co_u32_e32 v145, vcc, 0, v141, vcc
	s_nop 0
	s_nop 0
	s_waitcnt vmcnt(10)
	v_lshlrev_b32_e32 v150, 16, v216
	v_and_b32_e32 v151, 0xffff0000, v216
	v_lshlrev_b32_e32 v154, 16, v217
	v_and_b32_e32 v155, 0xffff0000, v217
	v_lshlrev_b32_e32 v146, 16, v218
	v_and_b32_e32 v147, 0xffff0000, v218
	v_add_f32_e32 v144, v68, v150
	v_mul_f32_e32 v144, 0xbfb8aa3b, v144
	v_exp_f32_e32 v144, v144
	v_lshlrev_b32_e32 v156, 16, v219
	v_and_b32_e32 v157, 0xffff0000, v219
	v_and_b32_e32 v153, 0xffff0000, v222
	v_add_f32_e32 v144, 1.0, v144
	v_rcp_f32_e32 v145, v144
	v_add_f32_e32 v144, v64, v146
	v_mul_f32_e32 v144, 0xbfb8aa3b, v144
	v_exp_f32_e32 v144, v144
	v_mul_f32_e32 v145, v72, v145
	v_exp_f32_e32 v146, v145
	v_add_f32_e32 v144, 1.0, v144
	v_rcp_f32_e32 v144, v144
	v_sub_f32_e32 v145, 1.0, v146
	v_add_f32_e32 v150, 1.0, v146
	v_mul_f32_e32 v145, v145, v150
	v_sqrt_f32_e32 v150, v145
	v_add_f32_e32 v145, v69, v151
	v_mul_f32_e32 v145, 0xbfb8aa3b, v145
	v_exp_f32_e32 v145, v145
	s_nop 0
	v_add_f32_e32 v145, 1.0, v145
	v_rcp_f32_e32 v151, v145
	v_add_f32_e32 v145, v65, v147
	v_mul_f32_e32 v145, 0xbfb8aa3b, v145
	v_exp_f32_e32 v145, v145
	v_mul_f32_e32 v147, v73, v151
	v_exp_f32_e32 v147, v147
	v_add_f32_e32 v145, 1.0, v145
	v_rcp_f32_e32 v145, v145
	v_sub_f32_e32 v151, 1.0, v147
	v_add_f32_e32 v152, 1.0, v147
	v_mul_f32_e32 v151, v151, v152
	v_sqrt_f32_e32 v151, v151
	v_lshlrev_b32_e32 v152, 16, v222
	v_pk_mul_f32 v[144:145], v[144:145], v[152:153]
	v_add_f32_e32 v148, v70, v154
	v_pk_mul_f32 v[144:145], v[144:145], v[150:151]
	v_mul_f32_e32 v148, 0xbfb8aa3b, v148
	v_pk_fma_f32 v[138:139], v[138:139], v[146:147], v[144:145]
	v_add_co_u32_e32 v144, vcc, s1, v140
	v_exp_f32_e32 v148, v148
	s_nop 0
	v_addc_co_u32_e32 v145, vcc, 0, v141, vcc
	v_add_f32_e32 v148, 1.0, v148
	v_rcp_f32_e32 v148, v148
	v_add_f32_e32 v150, v66, v156
	v_mul_f32_e32 v150, 0xbfb8aa3b, v150
	v_exp_f32_e32 v150, v150
	v_mul_f32_e32 v148, v74, v148
	v_exp_f32_e32 v152, v148
	s_mov_b32 s1, 0x21a06000
	v_add_f32_e32 v150, 1.0, v150
	v_rcp_f32_e32 v150, v150
	v_sub_f32_e32 v148, 1.0, v152
	v_add_f32_e32 v151, 1.0, v152
	v_mul_f32_e32 v148, v148, v151
	v_sqrt_f32_e32 v154, v148
	v_add_f32_e32 v148, v71, v155
	v_mul_f32_e32 v148, 0xbfb8aa3b, v148
	v_exp_f32_e32 v148, v148
	v_add_f32_e32 v151, v67, v157
	v_mul_f32_e32 v151, 0xbfb8aa3b, v151
	v_exp_f32_e32 v151, v151
	v_add_f32_e32 v148, 1.0, v148
	v_rcp_f32_e32 v148, v148
	v_add_f32_e32 v151, 1.0, v151
	v_rcp_f32_e32 v151, v151
	v_mul_f32_e32 v148, v75, v148
	v_exp_f32_e32 v153, v148
	v_lshlrev_b32_e32 v146, 16, v224
	v_sub_f32_e32 v148, 1.0, v153
	v_add_f32_e32 v155, 1.0, v153
	v_mul_f32_e32 v148, v148, v155
	v_sqrt_f32_e32 v155, v148
	v_lshlrev_b32_e32 v148, 16, v223
	v_and_b32_e32 v149, 0xffff0000, v223
	v_pk_mul_f32 v[148:149], v[150:151], v[148:149]
	v_and_b32_e32 v147, 0xffff0000, v224
	v_pk_mul_f32 v[148:149], v[148:149], v[154:155]
	v_pk_mul_f32 v[146:147], v[138:139], v[146:147]
	v_pk_fma_f32 v[136:137], v[136:137], v[152:153], v[148:149]
	v_cvt_pk_bf16_f32 v144, v146, v147
	v_lshlrev_b32_e32 v146, 16, v225
	v_and_b32_e32 v147, 0xffff0000, v225
	v_pk_mul_f32 v[146:147], v[136:137], v[146:147]
	s_nop 0
	v_cvt_pk_bf16_f32 v145, v146, v147
	v_add_co_u32_e32 v146, vcc, s1, v142
	s_mov_b32 s1, 0x23a0f000
	s_nop 0
	v_addc_co_u32_e32 v147, vcc, 0, v143, vcc
	global_store_dwordx2 v[146:147], v[144:145], off
	v_add_co_u32_e32 v144, vcc, s1, v140
	s_mov_b32 s1, 0x1fa07000
	s_nop 0
	v_addc_co_u32_e32 v145, vcc, 0, v141, vcc
	s_nop 0
	v_add_co_u32_e32 v148, vcc, s1, v142
	s_mov_b32 s1, 0x1ba0f000
	s_nop 0
	v_addc_co_u32_e32 v149, vcc, 0, v143, vcc
	v_add_co_u32_e32 v140, vcc, s1, v140
	s_waitcnt vmcnt(7)
	v_lshlrev_b32_e32 v150, 16, v226
	v_addc_co_u32_e32 v141, vcc, 0, v141, vcc
	v_and_b32_e32 v151, 0xffff0000, v226
	v_lshlrev_b32_e32 v154, 16, v227
	v_and_b32_e32 v155, 0xffff0000, v227
	v_lshlrev_b32_e32 v146, 16, v232
	v_and_b32_e32 v147, 0xffff0000, v232
	v_add_f32_e32 v144, v68, v150
	v_mul_f32_e32 v144, 0xbfb8aa3b, v144
	v_exp_f32_e32 v144, v144
	v_lshlrev_b32_e32 v156, 16, v233
	v_and_b32_e32 v157, 0xffff0000, v233
	v_and_b32_e32 v153, 0xffff0000, v234
	v_add_f32_e32 v144, 1.0, v144
	v_rcp_f32_e32 v145, v144
	v_add_f32_e32 v144, v64, v146
	v_mul_f32_e32 v144, 0xbfb8aa3b, v144
	v_exp_f32_e32 v144, v144
	v_mul_f32_e32 v145, v72, v145
	v_exp_f32_e32 v146, v145
	v_add_co_u32_e32 v142, vcc, 0x21a07000, v142
	v_add_f32_e32 v144, 1.0, v144
	v_sub_f32_e32 v145, 1.0, v146
	v_add_f32_e32 v150, 1.0, v146
	v_mul_f32_e32 v145, v145, v150
	v_sqrt_f32_e32 v150, v145
	v_add_f32_e32 v145, v69, v151
	v_mul_f32_e32 v145, 0xbfb8aa3b, v145
	v_exp_f32_e32 v145, v145
	v_rcp_f32_e32 v144, v144
	v_addc_co_u32_e32 v143, vcc, 0, v143, vcc
	v_add_f32_e32 v145, 1.0, v145
	v_rcp_f32_e32 v151, v145
	v_add_f32_e32 v145, v65, v147
	v_mul_f32_e32 v145, 0xbfb8aa3b, v145
	v_exp_f32_e32 v145, v145
	v_mul_f32_e32 v147, v73, v151
	v_exp_f32_e32 v147, v147
	v_add_f32_e32 v145, 1.0, v145
	v_rcp_f32_e32 v145, v145
	v_sub_f32_e32 v151, 1.0, v147
	v_add_f32_e32 v152, 1.0, v147
	v_mul_f32_e32 v151, v151, v152
	v_lshlrev_b32_e32 v152, 16, v234
	v_add_f32_e32 v148, v70, v154
	v_mul_f32_e32 v148, 0xbfb8aa3b, v148
	v_exp_f32_e32 v148, v148
	v_sqrt_f32_e32 v151, v151
	v_pk_mul_f32 v[144:145], v[144:145], v[152:153]
	v_add_f32_e32 v148, 1.0, v148
	v_rcp_f32_e32 v148, v148
	v_pk_mul_f32 v[144:145], v[144:145], v[150:151]
	v_add_f32_e32 v150, v66, v156
	v_mul_f32_e32 v150, 0xbfb8aa3b, v150
	v_mul_f32_e32 v148, v74, v148
	v_exp_f32_e32 v152, v148
	v_exp_f32_e32 v150, v150
	v_pk_fma_f32 v[138:139], v[138:139], v[146:147], v[144:145]
	v_sub_f32_e32 v148, 1.0, v152
	v_add_f32_e32 v151, 1.0, v152
	v_mul_f32_e32 v148, v148, v151
	v_sqrt_f32_e32 v154, v148
	v_add_f32_e32 v148, v71, v155
	v_mul_f32_e32 v148, 0xbfb8aa3b, v148
	v_exp_f32_e32 v148, v148
	v_add_f32_e32 v151, v67, v157
	v_mul_f32_e32 v151, 0xbfb8aa3b, v151
	v_exp_f32_e32 v151, v151
	v_add_f32_e32 v148, 1.0, v148
	v_rcp_f32_e32 v148, v148
	v_add_f32_e32 v150, 1.0, v150
	v_add_f32_e32 v151, 1.0, v151
	v_rcp_f32_e32 v150, v150
	v_mul_f32_e32 v148, v75, v148
	v_exp_f32_e32 v153, v148
	v_rcp_f32_e32 v151, v151
	v_lshlrev_b32_e32 v144, 16, v238
	v_and_b32_e32 v145, 0xffff0000, v238
	v_sub_f32_e32 v148, 1.0, v153
	v_add_f32_e32 v155, 1.0, v153
	v_mul_f32_e32 v148, v148, v155
	v_sqrt_f32_e32 v155, v148
	v_lshlrev_b32_e32 v148, 16, v235
	v_and_b32_e32 v149, 0xffff0000, v235
	v_pk_mul_f32 v[148:149], v[150:151], v[148:149]
	v_pk_mul_f32 v[144:145], v[138:139], v[144:145]
	v_pk_mul_f32 v[148:149], v[148:149], v[154:155]
	v_cvt_pk_bf16_f32 v140, v144, v145
	v_pk_fma_f32 v[136:137], v[136:137], v[152:153], v[148:149]
	v_lshlrev_b32_e32 v144, 16, v239
	v_and_b32_e32 v145, 0xffff0000, v239
	v_pk_mul_f32 v[144:145], v[136:137], v[144:145]
	s_nop 0
	v_cvt_pk_bf16_f32 v141, v144, v145
	global_store_dwordx2 v[142:143], v[140:141], off
	s_cbranch_scc0 .LBB0_1021
	v_add_u32_e32 v192, s96, v192
	s_mov_b32 s0, 0x1ffff
	v_cmp_lt_i32_e32 vcc, s0, v192
	v_mov_b64_e32 v[134:135], v[130:131]
	v_mov_b64_e32 v[138:139], v[122:123]
	v_mov_b64_e32 v[142:143], v[114:115]
	v_mov_b64_e32 v[150:151], v[106:107]
	v_mov_b64_e32 v[158:159], v[98:99]
	v_mov_b64_e32 v[166:167], v[90:91]
	v_mov_b64_e32 v[146:147], v[126:127]
	v_mov_b64_e32 v[154:155], v[118:119]
	v_mov_b64_e32 v[162:163], v[110:111]
	v_mov_b64_e32 v[170:171], v[102:103]
	v_mov_b64_e32 v[174:175], v[94:95]
	v_mov_b64_e32 v[178:179], v[86:87]
	v_add_u32_e32 v193, s2, v193
	s_or_b64 s[92:93], vcc, s[92:93]
	v_mov_b64_e32 v[132:133], v[128:129]
	v_mov_b64_e32 v[136:137], v[120:121]
	v_mov_b64_e32 v[140:141], v[112:113]
	v_mov_b64_e32 v[148:149], v[104:105]
	v_mov_b64_e32 v[156:157], v[96:97]
	v_mov_b64_e32 v[164:165], v[88:89]
	v_mov_b64_e32 v[144:145], v[124:125]
	v_mov_b64_e32 v[152:153], v[116:117]
	v_mov_b64_e32 v[160:161], v[108:109]
	v_mov_b64_e32 v[168:169], v[100:101]
	v_mov_b64_e32 v[172:173], v[92:93]
	v_mov_b64_e32 v[176:177], v[84:85]
	s_andn2_b64 exec, exec, s[92:93]
	s_cbranch_execnz .LBB0_976
